# grid barrier leader path: XCD generation published before the leader's own invalidate (on top of prep_item prefetch)
# baseline (speedup 1.0000x reference)
; __device__ __forceinline__ unsigned xb_add(unsigned* p, unsigned v) { return __hip_atomic_fetch_add(p, v, __ATOMIC_RELAXED, __HIP_MEMORY_SCOPE_AGENT); }
; __device__ __forceinline__ void xcd_barrier(const XcdBarrier& b) {
;     ...
;             __builtin_amdgcn_fence(__ATOMIC_ACQUIRE, "agent");
;             xb_add(&bar[XB_XGEN(b.x)], 1u);
;             asm volatile("s_waitcnt vmcnt(0)" ::: "memory");
.LBB0_96:
	s_or_b64 exec, exec, s[38:39]
	s_waitcnt vmcnt(0)
	global_atomic_add v[132:133], v176, off
	buffer_inv sc1
	s_waitcnt vmcnt(0)
